# RWKV static scan: next tile's first steps prefetched across the tile barrier (helper per-tile barriers doubled to certify staging is complete; compute waves take one extra barrier at step 24)
# baseline (speedup 1.0000x reference)
.LBB0_551:
	s_or_b64 exec, exec, s[52:53]
	s_lshl_b32 s30, s98, 2
	s_lshl_b32 s38, s98, 1
	s_and_b32 s30, s30, 0xf00
	s_and_b32 s40, s38, 0x780
	s_add_u32 s38, s70, s50
	s_addc_u32 s39, s71, 0
	v_lshl_add_u64 v[8:9], v[4:5], 1, s[38:39]
	s_add_u32 s38, s37, s30
	s_addc_u32 s39, 0, 0
	v_lshl_add_u64 v[12:13], s[26:27], 0, v[50:51]
	s_add_u32 s26, s36, s40
	s_addc_u32 s27, 0, 0
	v_lshl_add_u64 v[8:9], v[8:9], 0, v[60:61]
	v_lshl_add_u64 v[10:11], v[46:47], 0, s[38:39]
	v_lshl_add_u64 v[12:13], v[12:13], 0, s[26:27]
	v_add_u32_e32 v14, s36, v99
	s_mov_b64 s[52:53], 0
	s_mov_b32 s30, 0
	s_movk_i32 s36, 0x3fd0
	v_mov_b32_e32 v61, v77
	s_mov_b32 s37, 0
	s_waitcnt lgkmcnt(0)
	s_barrier
	s_barrier
	s_branch .LBB0_553
.LBB0_552:
	s_or_b64 exec, exec, s[26:27]
	s_add_u32 s52, s52, 0x11000
	s_mov_b64 s[26:27], 0x4000
	s_addc_u32 s53, s53, 0
	s_addk_i32 s30, 0x200
	s_sub_i32 s36, s36, 32
	v_lshl_add_u64 v[10:11], v[10:11], 0, s[26:27]
	s_cmp_eq_u32 s52, 0x21ef000
	v_add_u32_e32 v61, 32, v61
	s_waitcnt lgkmcnt(0)
	s_barrier
	s_barrier
	s_cbranch_scc1 .LBB0_580

.LBB0_583:
	s_or_b64 exec, exec, s[20:21]
	s_barrier
	s_barrier
	s_and_saveexec_b64 s[20:21], s[34:35]
	s_cbranch_execz .LBB0_585
	s_waitcnt vmcnt(0)
	ds_read_b128 v[0:3], v90
	ds_read_b128 v[6:9], v90 offset:16
	s_mov_b32 s51, s31
	v_mov_b32_e32 v61, v31
	s_waitcnt lgkmcnt(1)
	v_cvt_pk_bf16_f32 v0, v0, v1
	v_cvt_pk_bf16_f32 v1, v2, v3
	s_waitcnt lgkmcnt(0)
	v_cvt_pk_bf16_f32 v2, v6, v7
	v_add_u32_e32 v6, s93, v91
	v_mul_lo_u32 v30, v6, s33
	v_lshl_add_u64 v[6:7], s[70:71], 0, v[30:31]
	v_lshl_add_u64 v[6:7], v[6:7], 0, s[50:51]
	v_lshl_add_u64 v[4:5], v[4:5], 1, v[6:7]
	v_cvt_pk_bf16_f32 v3, v8, v9
	v_lshl_add_u64 v[4:5], v[4:5], 0, v[60:61]
	global_store_dwordx4 v[4:5], v[0:3], off offset:2048

.LBB0_586:
	s_andn2_saveexec_b64 s[20:21], s[48:49]
	s_cbranch_execz .LBB0_451
	s_setprio 2
	v_mov_b32_e32 v30, v31
	s_mov_b32 s26, 0
	s_mov_b64 s[22:23], 0
	s_waitcnt vmcnt(33)
	v_mov_b64_e32 v[16:17], v[30:31]
	s_waitcnt vmcnt(31)
	v_mov_b64_e32 v[18:19], v[30:31]
	s_barrier
	s_waitcnt vmcnt(0)
	s_and_b32 s30, s26, 1
	s_lshl_b32 s36, s30, 11
	s_lshl_b32 s37, s30, 15
	v_or_b32_e32 v30, s37, v69
	v_add_u32_e32 v49, s36, v92
	v_add_u32_e32 v1, s36, v94
	v_cndmask_b32_e64 v53, v93, v1, s[24:25]
	v_lshl_add_u32 v0, s30, 8, v95
	ds_read_b128 v[168:171], v30
	ds_read_b128 v[172:175], v30 offset:256
	ds_read_b128 v[176:179], v30 offset:512
	ds_read_b128 v[180:183], v30 offset:768
	ds_read_b128 v[64:67], v49
	ds_read_b128 v[184:187], v30 offset:1024
	ds_read_b128 v[188:191], v30 offset:1280
	ds_read_b128 v[192:195], v30 offset:1536
	ds_read_b128 v[196:199], v30 offset:1792
	ds_read_b128 v[200:203], v30 offset:2048
	ds_read_b128 v[204:207], v30 offset:2304
	ds_read_b128 v[208:211], v30 offset:2560
	ds_read_b128 v[212:215], v30 offset:2816
	ds_read_b128 v[108:111], v0
	s_lshl_b32 s27, s26, 5
	s_sub_i32 s27, 0x4010, s27
	s_min_u32 s27, s27, 32
	s_lshr_b32 s36, s27, 3
.LrwU_first:
	s_waitcnt lgkmcnt(5)
	v_pk_mul_f32 v[0:1], v[16:17], v[176:177]
	v_pk_fma_f32 v[12:13], v[64:65], v[172:173], v[16:17] op_sel_hi:[0,1,1]
	v_pk_fma_f32 v[0:1], v[18:19], v[178:179], v[0:1]
	v_pk_fma_f32 v[14:15], v[64:65], v[174:175], v[18:19] op_sel_hi:[0,1,1]
	v_add_f32_e32 v2, v0, v1
	ds_read_b128 v[216:219], v30 offset:3072
	ds_read_b128 v[220:223], v30 offset:3328
	v_add_f32_dpp v2, v2, v2 quad_perm:[1,0,3,2] row_mask:0xf bank_mask:0xf bound_ctrl:1
	ds_read_b128 v[224:227], v30 offset:3584
	ds_read_b128 v[228:231], v30 offset:3840
	v_add_f32_dpp v2, v2, v2 quad_perm:[2,3,0,1] row_mask:0xf bank_mask:0xf bound_ctrl:1
	s_nop 0
	s_nop 0
	v_add_f32_dpp v2, v2, v2 row_half_mirror row_mask:0xf bank_mask:0xf bound_ctrl:1
	s_nop 0
	s_nop 0
	v_add_f32_dpp v2, v2, v2 row_mirror row_mask:0xf bank_mask:0xf bound_ctrl:1
	ds_read_b128 v[104:107], v49 offset:16
	v_pk_fma_f32 v[12:13], v[2:3], v[180:181], v[12:13] op_sel_hi:[0,1,1] neg_lo:[1,0,0] neg_hi:[1,0,0]
	v_pk_fma_f32 v[14:15], v[2:3], v[182:183], v[14:15] op_sel_hi:[0,1,1] neg_lo:[1,0,0] neg_hi:[1,0,0]
	v_pk_mul_f32 v[0:1], v[12:13], v[192:193]
	v_pk_fma_f32 v[16:17], v[64:65], v[188:189], v[12:13] op_sel:[1,0,0]
	v_pk_fma_f32 v[0:1], v[14:15], v[194:195], v[0:1]
	v_pk_fma_f32 v[18:19], v[64:65], v[190:191], v[14:15] op_sel:[1,0,0]
	v_add_f32_e32 v2, v0, v1
	v_pk_mul_f32 v[4:5], v[168:169], v[12:13]
	v_pk_fma_f32 v[4:5], v[14:15], v[170:171], v[4:5]
	v_add_f32_dpp v2, v2, v2 quad_perm:[1,0,3,2] row_mask:0xf bank_mask:0xf bound_ctrl:1
	v_add_f32_e32 v8, v4, v5
	ds_read_b128 v[168:171], v30 offset:4096
	v_add_f32_dpp v2, v2, v2 quad_perm:[2,3,0,1] row_mask:0xf bank_mask:0xf bound_ctrl:1
	ds_read_b128 v[172:175], v30 offset:4352
	ds_read_b128 v[176:179], v30 offset:4608
	v_add_f32_dpp v2, v2, v2 row_half_mirror row_mask:0xf bank_mask:0xf bound_ctrl:1
	ds_read_b128 v[180:183], v30 offset:4864
	s_nop 0
	v_add_f32_dpp v2, v2, v2 row_mirror row_mask:0xf bank_mask:0xf bound_ctrl:1
	s_nop 0
	v_pk_fma_f32 v[16:17], v[2:3], v[196:197], v[16:17] op_sel_hi:[0,1,1] neg_lo:[1,0,0] neg_hi:[1,0,0]
	v_pk_fma_f32 v[18:19], v[2:3], v[198:199], v[18:19] op_sel_hi:[0,1,1] neg_lo:[1,0,0] neg_hi:[1,0,0]
	s_waitcnt lgkmcnt(5)
	v_pk_mul_f32 v[0:1], v[16:17], v[208:209]
	v_pk_fma_f32 v[12:13], v[66:67], v[204:205], v[16:17] op_sel_hi:[0,1,1]
	v_pk_fma_f32 v[0:1], v[18:19], v[210:211], v[0:1]
	v_pk_fma_f32 v[14:15], v[66:67], v[206:207], v[18:19] op_sel_hi:[0,1,1]
	v_add_f32_e32 v2, v0, v1
	v_pk_mul_f32 v[4:5], v[184:185], v[16:17]
	v_pk_fma_f32 v[4:5], v[18:19], v[186:187], v[4:5]
	v_add_f32_dpp v2, v2, v2 quad_perm:[1,0,3,2] row_mask:0xf bank_mask:0xf bound_ctrl:1
	v_add_f32_e32 v9, v4, v5
	ds_read_b128 v[184:187], v30 offset:5120
	v_add_f32_dpp v2, v2, v2 quad_perm:[2,3,0,1] row_mask:0xf bank_mask:0xf bound_ctrl:1
	ds_read_b128 v[188:191], v30 offset:5376
	ds_read_b128 v[192:195], v30 offset:5632
	v_add_f32_dpp v2, v2, v2 row_half_mirror row_mask:0xf bank_mask:0xf bound_ctrl:1
	ds_read_b128 v[196:199], v30 offset:5888
	s_nop 0
	v_add_f32_dpp v2, v2, v2 row_mirror row_mask:0xf bank_mask:0xf bound_ctrl:1
	s_nop 0
	v_pk_fma_f32 v[12:13], v[2:3], v[212:213], v[12:13] op_sel_hi:[0,1,1] neg_lo:[1,0,0] neg_hi:[1,0,0]
	v_pk_fma_f32 v[14:15], v[2:3], v[214:215], v[14:15] op_sel_hi:[0,1,1] neg_lo:[1,0,0] neg_hi:[1,0,0]
	v_pk_mul_f32 v[0:1], v[12:13], v[224:225]
	v_pk_fma_f32 v[16:17], v[66:67], v[220:221], v[12:13] op_sel:[1,0,0]
	v_pk_fma_f32 v[0:1], v[14:15], v[226:227], v[0:1]
	v_pk_fma_f32 v[18:19], v[66:67], v[222:223], v[14:15] op_sel:[1,0,0]
	v_add_f32_e32 v2, v0, v1
	v_pk_mul_f32 v[4:5], v[200:201], v[12:13]
	v_pk_fma_f32 v[4:5], v[14:15], v[202:203], v[4:5]
	v_add_f32_dpp v2, v2, v2 quad_perm:[1,0,3,2] row_mask:0xf bank_mask:0xf bound_ctrl:1
	v_add_f32_e32 v10, v4, v5
	ds_read_b128 v[200:203], v30 offset:6144
	v_add_f32_dpp v2, v2, v2 quad_perm:[2,3,0,1] row_mask:0xf bank_mask:0xf bound_ctrl:1
	ds_read_b128 v[204:207], v30 offset:6400
	ds_read_b128 v[208:211], v30 offset:6656
	v_add_f32_dpp v2, v2, v2 row_half_mirror row_mask:0xf bank_mask:0xf bound_ctrl:1
	ds_read_b128 v[212:215], v30 offset:6912
	s_nop 0
	v_add_f32_dpp v2, v2, v2 row_mirror row_mask:0xf bank_mask:0xf bound_ctrl:1
	s_nop 0
	v_pk_fma_f32 v[16:17], v[2:3], v[228:229], v[16:17] op_sel_hi:[0,1,1] neg_lo:[1,0,0] neg_hi:[1,0,0]
	v_pk_fma_f32 v[18:19], v[2:3], v[230:231], v[18:19] op_sel_hi:[0,1,1] neg_lo:[1,0,0] neg_hi:[1,0,0]
	s_waitcnt lgkmcnt(4)
	v_pk_mul_f32 v[0:1], v[16:17], v[176:177]
	v_pk_fma_f32 v[12:13], v[104:105], v[172:173], v[16:17] op_sel_hi:[0,1,1]
	v_pk_fma_f32 v[0:1], v[18:19], v[178:179], v[0:1]
	v_pk_fma_f32 v[14:15], v[104:105], v[174:175], v[18:19] op_sel_hi:[0,1,1]
	v_add_f32_e32 v2, v0, v1
	v_pk_mul_f32 v[4:5], v[216:217], v[16:17]
	v_pk_fma_f32 v[4:5], v[18:19], v[218:219], v[4:5]
	v_add_f32_dpp v2, v2, v2 quad_perm:[1,0,3,2] row_mask:0xf bank_mask:0xf bound_ctrl:1
	v_add_f32_e32 v11, v4, v5
	ds_read_b128 v[216:219], v30 offset:7168
	v_add_f32_dpp v2, v2, v2 quad_perm:[2,3,0,1] row_mask:0xf bank_mask:0xf bound_ctrl:1
	ds_read_b128 v[220:223], v30 offset:7424
	ds_read_b128 v[224:227], v30 offset:7680
	v_add_f32_dpp v2, v2, v2 row_half_mirror row_mask:0xf bank_mask:0xf bound_ctrl:1
	ds_read_b128 v[228:231], v30 offset:7936
	v_cndmask_b32_e64 v6, v9, v8, s[12:13]
	v_add_f32_dpp v2, v2, v2 row_mirror row_mask:0xf bank_mask:0xf bound_ctrl:1
	v_cndmask_b32_e64 v7, v8, v9, s[12:13]
	v_cndmask_b32_e64 v55, v11, v10, s[12:13]
	v_cndmask_b32_e64 v57, v10, v11, s[12:13]
	v_pk_fma_f32 v[12:13], v[2:3], v[180:181], v[12:13] op_sel_hi:[0,1,1] neg_lo:[1,0,0] neg_hi:[1,0,0]
	v_pk_fma_f32 v[14:15], v[2:3], v[182:183], v[14:15] op_sel_hi:[0,1,1] neg_lo:[1,0,0] neg_hi:[1,0,0]
	v_pk_mul_f32 v[0:1], v[12:13], v[192:193]
	v_pk_fma_f32 v[16:17], v[104:105], v[188:189], v[12:13] op_sel:[1,0,0]
	v_pk_fma_f32 v[0:1], v[14:15], v[194:195], v[0:1]
	v_pk_fma_f32 v[18:19], v[104:105], v[190:191], v[14:15] op_sel:[1,0,0]
	v_add_f32_e32 v2, v0, v1
	v_pk_mul_f32 v[4:5], v[168:169], v[12:13]
	v_pk_fma_f32 v[4:5], v[14:15], v[170:171], v[4:5]
	v_add_f32_dpp v2, v2, v2 quad_perm:[1,0,3,2] row_mask:0xf bank_mask:0xf bound_ctrl:1
	v_add_f32_e32 v24, v4, v5
	ds_read_b128 v[168:171], v30 offset:8192
	v_add_f32_dpp v2, v2, v2 quad_perm:[2,3,0,1] row_mask:0xf bank_mask:0xf bound_ctrl:1
	ds_read_b128 v[172:175], v30 offset:8448
	ds_read_b128 v[176:179], v30 offset:8704
	v_add_f32_dpp v2, v2, v2 row_half_mirror row_mask:0xf bank_mask:0xf bound_ctrl:1
	ds_read_b128 v[180:183], v30 offset:8960
	v_add_f32_dpp v6, v7, v6 quad_perm:[1,0,3,2] row_mask:0xf bank_mask:0xf bound_ctrl:1
	v_add_f32_dpp v2, v2, v2 row_mirror row_mask:0xf bank_mask:0xf bound_ctrl:1
	v_add_f32_dpp v55, v57, v55 quad_perm:[1,0,3,2] row_mask:0xf bank_mask:0xf bound_ctrl:1
	v_cndmask_b32_e64 v57, v6, v55, s[14:15]
	v_cndmask_b32_e64 v7, v55, v6, s[14:15]
	v_pk_fma_f32 v[16:17], v[2:3], v[196:197], v[16:17] op_sel_hi:[0,1,1] neg_lo:[1,0,0] neg_hi:[1,0,0]
	v_pk_fma_f32 v[18:19], v[2:3], v[198:199], v[18:19] op_sel_hi:[0,1,1] neg_lo:[1,0,0] neg_hi:[1,0,0]
	s_waitcnt lgkmcnt(4)
	v_pk_mul_f32 v[0:1], v[16:17], v[208:209]
	v_pk_fma_f32 v[12:13], v[106:107], v[204:205], v[16:17] op_sel_hi:[0,1,1]
	v_pk_fma_f32 v[0:1], v[18:19], v[210:211], v[0:1]
	v_pk_fma_f32 v[14:15], v[106:107], v[206:207], v[18:19] op_sel_hi:[0,1,1]
	v_add_f32_e32 v2, v0, v1
	v_pk_mul_f32 v[4:5], v[184:185], v[16:17]
	v_pk_fma_f32 v[4:5], v[18:19], v[186:187], v[4:5]
	v_add_f32_dpp v2, v2, v2 quad_perm:[1,0,3,2] row_mask:0xf bank_mask:0xf bound_ctrl:1
	v_add_f32_e32 v25, v4, v5
	ds_read_b128 v[184:187], v30 offset:9216
	v_add_f32_dpp v2, v2, v2 quad_perm:[2,3,0,1] row_mask:0xf bank_mask:0xf bound_ctrl:1
	ds_read_b128 v[188:191], v30 offset:9472
	ds_read_b128 v[192:195], v30 offset:9728
	v_add_f32_dpp v2, v2, v2 row_half_mirror row_mask:0xf bank_mask:0xf bound_ctrl:1
	ds_read_b128 v[196:199], v30 offset:9984
	v_add_f32_dpp v7, v57, v7 quad_perm:[2,3,0,1] row_mask:0xf bank_mask:0xf bound_ctrl:1
	v_add_f32_dpp v2, v2, v2 row_mirror row_mask:0xf bank_mask:0xf bound_ctrl:1
	ds_read_b128 v[64:67], v49 offset:32
	v_add_u32_e32 v49, 32, v49
	v_add_f32_dpp v7, v7, v7 row_ror:4 row_mask:0xf bank_mask:0xf bound_ctrl:1
	v_pk_fma_f32 v[12:13], v[2:3], v[212:213], v[12:13] op_sel_hi:[0,1,1] neg_lo:[1,0,0] neg_hi:[1,0,0]
	v_pk_fma_f32 v[14:15], v[2:3], v[214:215], v[14:15] op_sel_hi:[0,1,1] neg_lo:[1,0,0] neg_hi:[1,0,0]
	v_pk_mul_f32 v[0:1], v[12:13], v[224:225]
	v_pk_fma_f32 v[16:17], v[106:107], v[220:221], v[12:13] op_sel:[1,0,0]
	v_pk_fma_f32 v[0:1], v[14:15], v[226:227], v[0:1]
	v_pk_fma_f32 v[18:19], v[106:107], v[222:223], v[14:15] op_sel:[1,0,0]
	v_add_f32_e32 v2, v0, v1
	v_pk_mul_f32 v[4:5], v[200:201], v[12:13]
	v_pk_fma_f32 v[4:5], v[14:15], v[202:203], v[4:5]
	v_add_f32_dpp v2, v2, v2 quad_perm:[1,0,3,2] row_mask:0xf bank_mask:0xf bound_ctrl:1
	v_add_f32_e32 v26, v4, v5
	ds_read_b128 v[200:203], v30 offset:10240
	v_add_f32_dpp v2, v2, v2 quad_perm:[2,3,0,1] row_mask:0xf bank_mask:0xf bound_ctrl:1
	ds_read_b128 v[204:207], v30 offset:10496
	ds_read_b128 v[208:211], v30 offset:10752
	v_add_f32_dpp v2, v2, v2 row_half_mirror row_mask:0xf bank_mask:0xf bound_ctrl:1
	ds_read_b128 v[212:215], v30 offset:11008
	v_add_f32_dpp v7, v7, v7 row_ror:8 row_mask:0xf bank_mask:0xf bound_ctrl:1
	v_add_f32_dpp v2, v2, v2 row_mirror row_mask:0xf bank_mask:0xf bound_ctrl:1
	ds_write_b32 v53, v7
	v_pk_fma_f32 v[16:17], v[2:3], v[228:229], v[16:17] op_sel_hi:[0,1,1] neg_lo:[1,0,0] neg_hi:[1,0,0]
	v_pk_fma_f32 v[18:19], v[2:3], v[230:231], v[18:19] op_sel_hi:[0,1,1] neg_lo:[1,0,0] neg_hi:[1,0,0]
	v_add_u32_e32 v30, 0x2000, v30
	s_cmp_eq_u32 s36, 2
	s_cbranch_scc1 .LrwU_last
	s_waitcnt lgkmcnt(5)
	v_pk_mul_f32 v[0:1], v[16:17], v[176:177]
	v_pk_fma_f32 v[12:13], v[64:65], v[172:173], v[16:17] op_sel_hi:[0,1,1]
	v_pk_fma_f32 v[0:1], v[18:19], v[178:179], v[0:1]
	v_pk_fma_f32 v[14:15], v[64:65], v[174:175], v[18:19] op_sel_hi:[0,1,1]
	v_add_f32_e32 v2, v0, v1
	v_pk_mul_f32 v[4:5], v[216:217], v[16:17]
	v_pk_fma_f32 v[4:5], v[18:19], v[218:219], v[4:5]
	v_add_f32_dpp v2, v2, v2 quad_perm:[1,0,3,2] row_mask:0xf bank_mask:0xf bound_ctrl:1
	v_add_f32_e32 v27, v4, v5
	ds_read_b128 v[216:219], v30 offset:3072
	v_add_f32_dpp v2, v2, v2 quad_perm:[2,3,0,1] row_mask:0xf bank_mask:0xf bound_ctrl:1
	ds_read_b128 v[220:223], v30 offset:3328
	ds_read_b128 v[224:227], v30 offset:3584
	v_add_f32_dpp v2, v2, v2 row_half_mirror row_mask:0xf bank_mask:0xf bound_ctrl:1
	ds_read_b128 v[228:231], v30 offset:3840
	v_cndmask_b32_e64 v6, v25, v24, s[12:13]
	v_add_f32_dpp v2, v2, v2 row_mirror row_mask:0xf bank_mask:0xf bound_ctrl:1
	v_cndmask_b32_e64 v7, v24, v25, s[12:13]
	v_cndmask_b32_e64 v55, v27, v26, s[12:13]
	v_cndmask_b32_e64 v57, v26, v27, s[12:13]
	v_pk_fma_f32 v[12:13], v[2:3], v[180:181], v[12:13] op_sel_hi:[0,1,1] neg_lo:[1,0,0] neg_hi:[1,0,0]
	v_pk_fma_f32 v[14:15], v[2:3], v[182:183], v[14:15] op_sel_hi:[0,1,1] neg_lo:[1,0,0] neg_hi:[1,0,0]
	v_pk_mul_f32 v[0:1], v[12:13], v[192:193]
	v_pk_fma_f32 v[16:17], v[64:65], v[188:189], v[12:13] op_sel:[1,0,0]
	v_pk_fma_f32 v[0:1], v[14:15], v[194:195], v[0:1]
	v_pk_fma_f32 v[18:19], v[64:65], v[190:191], v[14:15] op_sel:[1,0,0]
	v_add_f32_e32 v2, v0, v1
	v_pk_mul_f32 v[4:5], v[168:169], v[12:13]
	v_pk_fma_f32 v[4:5], v[14:15], v[170:171], v[4:5]
	v_add_f32_dpp v2, v2, v2 quad_perm:[1,0,3,2] row_mask:0xf bank_mask:0xf bound_ctrl:1
	v_add_f32_e32 v8, v4, v5
	ds_read_b128 v[168:171], v30 offset:4096
	v_add_f32_dpp v2, v2, v2 quad_perm:[2,3,0,1] row_mask:0xf bank_mask:0xf bound_ctrl:1
	ds_read_b128 v[172:175], v30 offset:4352
	ds_read_b128 v[176:179], v30 offset:4608
	v_add_f32_dpp v2, v2, v2 row_half_mirror row_mask:0xf bank_mask:0xf bound_ctrl:1
	ds_read_b128 v[180:183], v30 offset:4864
	v_add_f32_dpp v6, v7, v6 quad_perm:[1,0,3,2] row_mask:0xf bank_mask:0xf bound_ctrl:1
	v_add_f32_dpp v2, v2, v2 row_mirror row_mask:0xf bank_mask:0xf bound_ctrl:1
	v_add_f32_dpp v55, v57, v55 quad_perm:[1,0,3,2] row_mask:0xf bank_mask:0xf bound_ctrl:1
	v_cndmask_b32_e64 v57, v6, v55, s[14:15]
	v_cndmask_b32_e64 v7, v55, v6, s[14:15]
	v_pk_fma_f32 v[16:17], v[2:3], v[196:197], v[16:17] op_sel_hi:[0,1,1] neg_lo:[1,0,0] neg_hi:[1,0,0]
	v_pk_fma_f32 v[18:19], v[2:3], v[198:199], v[18:19] op_sel_hi:[0,1,1] neg_lo:[1,0,0] neg_hi:[1,0,0]
	s_waitcnt lgkmcnt(4)
	v_pk_mul_f32 v[0:1], v[16:17], v[208:209]
	v_pk_fma_f32 v[12:13], v[66:67], v[204:205], v[16:17] op_sel_hi:[0,1,1]
	v_pk_fma_f32 v[0:1], v[18:19], v[210:211], v[0:1]
	v_pk_fma_f32 v[14:15], v[66:67], v[206:207], v[18:19] op_sel_hi:[0,1,1]
	v_add_f32_e32 v2, v0, v1
	v_pk_mul_f32 v[4:5], v[184:185], v[16:17]
	v_pk_fma_f32 v[4:5], v[18:19], v[186:187], v[4:5]
	v_add_f32_dpp v2, v2, v2 quad_perm:[1,0,3,2] row_mask:0xf bank_mask:0xf bound_ctrl:1
	v_add_f32_e32 v9, v4, v5
	ds_read_b128 v[184:187], v30 offset:5120
	v_add_f32_dpp v2, v2, v2 quad_perm:[2,3,0,1] row_mask:0xf bank_mask:0xf bound_ctrl:1
	ds_read_b128 v[188:191], v30 offset:5376
	ds_read_b128 v[192:195], v30 offset:5632
	v_add_f32_dpp v2, v2, v2 row_half_mirror row_mask:0xf bank_mask:0xf bound_ctrl:1
	ds_read_b128 v[196:199], v30 offset:5888
	v_add_f32_dpp v7, v57, v7 quad_perm:[2,3,0,1] row_mask:0xf bank_mask:0xf bound_ctrl:1
	v_add_f32_dpp v2, v2, v2 row_mirror row_mask:0xf bank_mask:0xf bound_ctrl:1
	ds_read_b128 v[104:107], v49 offset:16
	v_add_f32_dpp v7, v7, v7 row_ror:4 row_mask:0xf bank_mask:0xf bound_ctrl:1
	v_pk_fma_f32 v[12:13], v[2:3], v[212:213], v[12:13] op_sel_hi:[0,1,1] neg_lo:[1,0,0] neg_hi:[1,0,0]
	v_pk_fma_f32 v[14:15], v[2:3], v[214:215], v[14:15] op_sel_hi:[0,1,1] neg_lo:[1,0,0] neg_hi:[1,0,0]
	v_pk_mul_f32 v[0:1], v[12:13], v[224:225]
	v_pk_fma_f32 v[16:17], v[66:67], v[220:221], v[12:13] op_sel:[1,0,0]
	v_pk_fma_f32 v[0:1], v[14:15], v[226:227], v[0:1]
	v_pk_fma_f32 v[18:19], v[66:67], v[222:223], v[14:15] op_sel:[1,0,0]
	v_add_f32_e32 v2, v0, v1
	v_pk_mul_f32 v[4:5], v[200:201], v[12:13]
	v_pk_fma_f32 v[4:5], v[14:15], v[202:203], v[4:5]
	v_add_f32_dpp v2, v2, v2 quad_perm:[1,0,3,2] row_mask:0xf bank_mask:0xf bound_ctrl:1
	v_add_f32_e32 v10, v4, v5
	ds_read_b128 v[200:203], v30 offset:6144
	v_add_f32_dpp v2, v2, v2 quad_perm:[2,3,0,1] row_mask:0xf bank_mask:0xf bound_ctrl:1
	ds_read_b128 v[204:207], v30 offset:6400
	ds_read_b128 v[208:211], v30 offset:6656
	v_add_f32_dpp v2, v2, v2 row_half_mirror row_mask:0xf bank_mask:0xf bound_ctrl:1
	ds_read_b128 v[212:215], v30 offset:6912
	v_add_f32_dpp v7, v7, v7 row_ror:8 row_mask:0xf bank_mask:0xf bound_ctrl:1
	v_add_f32_dpp v2, v2, v2 row_mirror row_mask:0xf bank_mask:0xf bound_ctrl:1
	ds_write_b32 v53, v7 offset:256
	v_add_u32_e32 v53, 0x200, v53
	v_pk_fma_f32 v[16:17], v[2:3], v[228:229], v[16:17] op_sel_hi:[0,1,1] neg_lo:[1,0,0] neg_hi:[1,0,0]
	v_pk_fma_f32 v[18:19], v[2:3], v[230:231], v[18:19] op_sel_hi:[0,1,1] neg_lo:[1,0,0] neg_hi:[1,0,0]
	s_waitcnt lgkmcnt(5)
	v_pk_mul_f32 v[0:1], v[16:17], v[176:177]
	v_pk_fma_f32 v[12:13], v[104:105], v[172:173], v[16:17] op_sel_hi:[0,1,1]
	v_pk_fma_f32 v[0:1], v[18:19], v[178:179], v[0:1]
	v_pk_fma_f32 v[14:15], v[104:105], v[174:175], v[18:19] op_sel_hi:[0,1,1]
	v_add_f32_e32 v2, v0, v1
	v_pk_mul_f32 v[4:5], v[216:217], v[16:17]
	v_pk_fma_f32 v[4:5], v[18:19], v[218:219], v[4:5]
	v_add_f32_dpp v2, v2, v2 quad_perm:[1,0,3,2] row_mask:0xf bank_mask:0xf bound_ctrl:1
	v_add_f32_e32 v11, v4, v5
	ds_read_b128 v[216:219], v30 offset:7168
	v_add_f32_dpp v2, v2, v2 quad_perm:[2,3,0,1] row_mask:0xf bank_mask:0xf bound_ctrl:1
	ds_read_b128 v[220:223], v30 offset:7424
	ds_read_b128 v[224:227], v30 offset:7680
	v_add_f32_dpp v2, v2, v2 row_half_mirror row_mask:0xf bank_mask:0xf bound_ctrl:1
	ds_read_b128 v[228:231], v30 offset:7936
	v_cndmask_b32_e64 v6, v9, v8, s[12:13]
	v_add_f32_dpp v2, v2, v2 row_mirror row_mask:0xf bank_mask:0xf bound_ctrl:1
	v_cndmask_b32_e64 v7, v8, v9, s[12:13]
	v_cndmask_b32_e64 v55, v11, v10, s[12:13]
	v_cndmask_b32_e64 v57, v10, v11, s[12:13]
	v_pk_fma_f32 v[12:13], v[2:3], v[180:181], v[12:13] op_sel_hi:[0,1,1] neg_lo:[1,0,0] neg_hi:[1,0,0]
	v_pk_fma_f32 v[14:15], v[2:3], v[182:183], v[14:15] op_sel_hi:[0,1,1] neg_lo:[1,0,0] neg_hi:[1,0,0]
	v_pk_mul_f32 v[0:1], v[12:13], v[192:193]
	v_pk_fma_f32 v[16:17], v[104:105], v[188:189], v[12:13] op_sel:[1,0,0]
	v_pk_fma_f32 v[0:1], v[14:15], v[194:195], v[0:1]
	v_pk_fma_f32 v[18:19], v[104:105], v[190:191], v[14:15] op_sel:[1,0,0]
	v_add_f32_e32 v2, v0, v1
	v_pk_mul_f32 v[4:5], v[168:169], v[12:13]
	v_pk_fma_f32 v[4:5], v[14:15], v[170:171], v[4:5]
	v_add_f32_dpp v2, v2, v2 quad_perm:[1,0,3,2] row_mask:0xf bank_mask:0xf bound_ctrl:1
	v_add_f32_e32 v24, v4, v5
	ds_read_b128 v[168:171], v30 offset:8192
	v_add_f32_dpp v2, v2, v2 quad_perm:[2,3,0,1] row_mask:0xf bank_mask:0xf bound_ctrl:1
	ds_read_b128 v[172:175], v30 offset:8448
	ds_read_b128 v[176:179], v30 offset:8704
	v_add_f32_dpp v2, v2, v2 row_half_mirror row_mask:0xf bank_mask:0xf bound_ctrl:1
	ds_read_b128 v[180:183], v30 offset:8960
	v_add_f32_dpp v6, v7, v6 quad_perm:[1,0,3,2] row_mask:0xf bank_mask:0xf bound_ctrl:1
	v_add_f32_dpp v2, v2, v2 row_mirror row_mask:0xf bank_mask:0xf bound_ctrl:1
	v_add_f32_dpp v55, v57, v55 quad_perm:[1,0,3,2] row_mask:0xf bank_mask:0xf bound_ctrl:1
	v_cndmask_b32_e64 v57, v6, v55, s[14:15]
	v_cndmask_b32_e64 v7, v55, v6, s[14:15]
	v_pk_fma_f32 v[16:17], v[2:3], v[196:197], v[16:17] op_sel_hi:[0,1,1] neg_lo:[1,0,0] neg_hi:[1,0,0]
	v_pk_fma_f32 v[18:19], v[2:3], v[198:199], v[18:19] op_sel_hi:[0,1,1] neg_lo:[1,0,0] neg_hi:[1,0,0]
	s_waitcnt lgkmcnt(4)
	v_pk_mul_f32 v[0:1], v[16:17], v[208:209]
	v_pk_fma_f32 v[12:13], v[106:107], v[204:205], v[16:17] op_sel_hi:[0,1,1]
	v_pk_fma_f32 v[0:1], v[18:19], v[210:211], v[0:1]
	v_pk_fma_f32 v[14:15], v[106:107], v[206:207], v[18:19] op_sel_hi:[0,1,1]
	v_add_f32_e32 v2, v0, v1
	v_pk_mul_f32 v[4:5], v[184:185], v[16:17]
	v_pk_fma_f32 v[4:5], v[18:19], v[186:187], v[4:5]
	v_add_f32_dpp v2, v2, v2 quad_perm:[1,0,3,2] row_mask:0xf bank_mask:0xf bound_ctrl:1
	v_add_f32_e32 v25, v4, v5
	ds_read_b128 v[184:187], v30 offset:9216
	v_add_f32_dpp v2, v2, v2 quad_perm:[2,3,0,1] row_mask:0xf bank_mask:0xf bound_ctrl:1
	ds_read_b128 v[188:191], v30 offset:9472
	ds_read_b128 v[192:195], v30 offset:9728
	v_add_f32_dpp v2, v2, v2 row_half_mirror row_mask:0xf bank_mask:0xf bound_ctrl:1
	ds_read_b128 v[196:199], v30 offset:9984
	v_add_f32_dpp v7, v57, v7 quad_perm:[2,3,0,1] row_mask:0xf bank_mask:0xf bound_ctrl:1
	v_add_f32_dpp v2, v2, v2 row_mirror row_mask:0xf bank_mask:0xf bound_ctrl:1
	ds_read_b128 v[64:67], v49 offset:32
	v_add_u32_e32 v49, 32, v49
	v_add_f32_dpp v7, v7, v7 row_ror:4 row_mask:0xf bank_mask:0xf bound_ctrl:1
	v_pk_fma_f32 v[12:13], v[2:3], v[212:213], v[12:13] op_sel_hi:[0,1,1] neg_lo:[1,0,0] neg_hi:[1,0,0]
	v_pk_fma_f32 v[14:15], v[2:3], v[214:215], v[14:15] op_sel_hi:[0,1,1] neg_lo:[1,0,0] neg_hi:[1,0,0]
	v_pk_mul_f32 v[0:1], v[12:13], v[224:225]
	v_pk_fma_f32 v[16:17], v[106:107], v[220:221], v[12:13] op_sel:[1,0,0]
	v_pk_fma_f32 v[0:1], v[14:15], v[226:227], v[0:1]
	v_pk_fma_f32 v[18:19], v[106:107], v[222:223], v[14:15] op_sel:[1,0,0]
	v_add_f32_e32 v2, v0, v1
	v_pk_mul_f32 v[4:5], v[200:201], v[12:13]
	v_pk_fma_f32 v[4:5], v[14:15], v[202:203], v[4:5]
	v_add_f32_dpp v2, v2, v2 quad_perm:[1,0,3,2] row_mask:0xf bank_mask:0xf bound_ctrl:1
	v_add_f32_e32 v26, v4, v5
	ds_read_b128 v[200:203], v30 offset:10240
	v_add_f32_dpp v2, v2, v2 quad_perm:[2,3,0,1] row_mask:0xf bank_mask:0xf bound_ctrl:1
	ds_read_b128 v[204:207], v30 offset:10496
	ds_read_b128 v[208:211], v30 offset:10752
	v_add_f32_dpp v2, v2, v2 row_half_mirror row_mask:0xf bank_mask:0xf bound_ctrl:1
	ds_read_b128 v[212:215], v30 offset:11008
	v_add_f32_dpp v7, v7, v7 row_ror:8 row_mask:0xf bank_mask:0xf bound_ctrl:1
	v_add_f32_dpp v2, v2, v2 row_mirror row_mask:0xf bank_mask:0xf bound_ctrl:1
	ds_write_b32 v53, v7
	v_pk_fma_f32 v[16:17], v[2:3], v[228:229], v[16:17] op_sel_hi:[0,1,1] neg_lo:[1,0,0] neg_hi:[1,0,0]
	v_pk_fma_f32 v[18:19], v[2:3], v[230:231], v[18:19] op_sel_hi:[0,1,1] neg_lo:[1,0,0] neg_hi:[1,0,0]
	v_add_u32_e32 v30, 0x2000, v30
	s_waitcnt lgkmcnt(5)
	v_pk_mul_f32 v[0:1], v[16:17], v[176:177]
	v_pk_fma_f32 v[12:13], v[64:65], v[172:173], v[16:17] op_sel_hi:[0,1,1]
	v_pk_fma_f32 v[0:1], v[18:19], v[178:179], v[0:1]
	v_pk_fma_f32 v[14:15], v[64:65], v[174:175], v[18:19] op_sel_hi:[0,1,1]
	v_add_f32_e32 v2, v0, v1
	v_pk_mul_f32 v[4:5], v[216:217], v[16:17]
	v_pk_fma_f32 v[4:5], v[18:19], v[218:219], v[4:5]
	v_add_f32_dpp v2, v2, v2 quad_perm:[1,0,3,2] row_mask:0xf bank_mask:0xf bound_ctrl:1
	v_add_f32_e32 v27, v4, v5
	ds_read_b128 v[216:219], v30 offset:3072
	v_add_f32_dpp v2, v2, v2 quad_perm:[2,3,0,1] row_mask:0xf bank_mask:0xf bound_ctrl:1
	ds_read_b128 v[220:223], v30 offset:3328
	ds_read_b128 v[224:227], v30 offset:3584
	v_add_f32_dpp v2, v2, v2 row_half_mirror row_mask:0xf bank_mask:0xf bound_ctrl:1
	ds_read_b128 v[228:231], v30 offset:3840
	v_cndmask_b32_e64 v6, v25, v24, s[12:13]
	v_add_f32_dpp v2, v2, v2 row_mirror row_mask:0xf bank_mask:0xf bound_ctrl:1
	v_cndmask_b32_e64 v7, v24, v25, s[12:13]
	v_cndmask_b32_e64 v55, v27, v26, s[12:13]
	v_cndmask_b32_e64 v57, v26, v27, s[12:13]
	v_pk_fma_f32 v[12:13], v[2:3], v[180:181], v[12:13] op_sel_hi:[0,1,1] neg_lo:[1,0,0] neg_hi:[1,0,0]
	v_pk_fma_f32 v[14:15], v[2:3], v[182:183], v[14:15] op_sel_hi:[0,1,1] neg_lo:[1,0,0] neg_hi:[1,0,0]
	v_pk_mul_f32 v[0:1], v[12:13], v[192:193]
	v_pk_fma_f32 v[16:17], v[64:65], v[188:189], v[12:13] op_sel:[1,0,0]
	v_pk_fma_f32 v[0:1], v[14:15], v[194:195], v[0:1]
	v_pk_fma_f32 v[18:19], v[64:65], v[190:191], v[14:15] op_sel:[1,0,0]
	v_add_f32_e32 v2, v0, v1
	v_pk_mul_f32 v[4:5], v[168:169], v[12:13]
	v_pk_fma_f32 v[4:5], v[14:15], v[170:171], v[4:5]
	v_add_f32_dpp v2, v2, v2 quad_perm:[1,0,3,2] row_mask:0xf bank_mask:0xf bound_ctrl:1
	v_add_f32_e32 v8, v4, v5
	ds_read_b128 v[168:171], v30 offset:4096
	v_add_f32_dpp v2, v2, v2 quad_perm:[2,3,0,1] row_mask:0xf bank_mask:0xf bound_ctrl:1
	ds_read_b128 v[172:175], v30 offset:4352
	ds_read_b128 v[176:179], v30 offset:4608
	v_add_f32_dpp v2, v2, v2 row_half_mirror row_mask:0xf bank_mask:0xf bound_ctrl:1
	ds_read_b128 v[180:183], v30 offset:4864
	v_add_f32_dpp v6, v7, v6 quad_perm:[1,0,3,2] row_mask:0xf bank_mask:0xf bound_ctrl:1
	v_add_f32_dpp v2, v2, v2 row_mirror row_mask:0xf bank_mask:0xf bound_ctrl:1
	v_add_f32_dpp v55, v57, v55 quad_perm:[1,0,3,2] row_mask:0xf bank_mask:0xf bound_ctrl:1
	v_cndmask_b32_e64 v57, v6, v55, s[14:15]
	v_cndmask_b32_e64 v7, v55, v6, s[14:15]
	v_pk_fma_f32 v[16:17], v[2:3], v[196:197], v[16:17] op_sel_hi:[0,1,1] neg_lo:[1,0,0] neg_hi:[1,0,0]
	v_pk_fma_f32 v[18:19], v[2:3], v[198:199], v[18:19] op_sel_hi:[0,1,1] neg_lo:[1,0,0] neg_hi:[1,0,0]
	s_waitcnt lgkmcnt(4)
	v_pk_mul_f32 v[0:1], v[16:17], v[208:209]
	v_pk_fma_f32 v[12:13], v[66:67], v[204:205], v[16:17] op_sel_hi:[0,1,1]
	v_pk_fma_f32 v[0:1], v[18:19], v[210:211], v[0:1]
	v_pk_fma_f32 v[14:15], v[66:67], v[206:207], v[18:19] op_sel_hi:[0,1,1]
	v_add_f32_e32 v2, v0, v1
	v_pk_mul_f32 v[4:5], v[184:185], v[16:17]
	v_pk_fma_f32 v[4:5], v[18:19], v[186:187], v[4:5]
	v_add_f32_dpp v2, v2, v2 quad_perm:[1,0,3,2] row_mask:0xf bank_mask:0xf bound_ctrl:1
	v_add_f32_e32 v9, v4, v5
	ds_read_b128 v[184:187], v30 offset:5120
	v_add_f32_dpp v2, v2, v2 quad_perm:[2,3,0,1] row_mask:0xf bank_mask:0xf bound_ctrl:1
	ds_read_b128 v[188:191], v30 offset:5376
	ds_read_b128 v[192:195], v30 offset:5632
	v_add_f32_dpp v2, v2, v2 row_half_mirror row_mask:0xf bank_mask:0xf bound_ctrl:1
	ds_read_b128 v[196:199], v30 offset:5888
	v_add_f32_dpp v7, v57, v7 quad_perm:[2,3,0,1] row_mask:0xf bank_mask:0xf bound_ctrl:1
	v_add_f32_dpp v2, v2, v2 row_mirror row_mask:0xf bank_mask:0xf bound_ctrl:1
	ds_read_b128 v[104:107], v49 offset:16
	v_add_f32_dpp v7, v7, v7 row_ror:4 row_mask:0xf bank_mask:0xf bound_ctrl:1
	v_pk_fma_f32 v[12:13], v[2:3], v[212:213], v[12:13] op_sel_hi:[0,1,1] neg_lo:[1,0,0] neg_hi:[1,0,0]
	v_pk_fma_f32 v[14:15], v[2:3], v[214:215], v[14:15] op_sel_hi:[0,1,1] neg_lo:[1,0,0] neg_hi:[1,0,0]
	v_pk_mul_f32 v[0:1], v[12:13], v[224:225]
	v_pk_fma_f32 v[16:17], v[66:67], v[220:221], v[12:13] op_sel:[1,0,0]
	v_pk_fma_f32 v[0:1], v[14:15], v[226:227], v[0:1]
	v_pk_fma_f32 v[18:19], v[66:67], v[222:223], v[14:15] op_sel:[1,0,0]
	v_add_f32_e32 v2, v0, v1
	v_pk_mul_f32 v[4:5], v[200:201], v[12:13]
	v_pk_fma_f32 v[4:5], v[14:15], v[202:203], v[4:5]
	v_add_f32_dpp v2, v2, v2 quad_perm:[1,0,3,2] row_mask:0xf bank_mask:0xf bound_ctrl:1
	v_add_f32_e32 v10, v4, v5
	ds_read_b128 v[200:203], v30 offset:6144
	v_add_f32_dpp v2, v2, v2 quad_perm:[2,3,0,1] row_mask:0xf bank_mask:0xf bound_ctrl:1
	ds_read_b128 v[204:207], v30 offset:6400
	ds_read_b128 v[208:211], v30 offset:6656
	v_add_f32_dpp v2, v2, v2 row_half_mirror row_mask:0xf bank_mask:0xf bound_ctrl:1
	ds_read_b128 v[212:215], v30 offset:6912
	v_add_f32_dpp v7, v7, v7 row_ror:8 row_mask:0xf bank_mask:0xf bound_ctrl:1
	v_add_f32_dpp v2, v2, v2 row_mirror row_mask:0xf bank_mask:0xf bound_ctrl:1
	ds_write_b32 v53, v7 offset:256
	v_add_u32_e32 v53, 0x200, v53
	v_pk_fma_f32 v[16:17], v[2:3], v[228:229], v[16:17] op_sel_hi:[0,1,1] neg_lo:[1,0,0] neg_hi:[1,0,0]
	v_pk_fma_f32 v[18:19], v[2:3], v[230:231], v[18:19] op_sel_hi:[0,1,1] neg_lo:[1,0,0] neg_hi:[1,0,0]
	s_waitcnt lgkmcnt(5)
	v_pk_mul_f32 v[0:1], v[16:17], v[176:177]
	v_pk_fma_f32 v[12:13], v[104:105], v[172:173], v[16:17] op_sel_hi:[0,1,1]
	v_pk_fma_f32 v[0:1], v[18:19], v[178:179], v[0:1]
	v_pk_fma_f32 v[14:15], v[104:105], v[174:175], v[18:19] op_sel_hi:[0,1,1]
	v_add_f32_e32 v2, v0, v1
	v_pk_mul_f32 v[4:5], v[216:217], v[16:17]
	v_pk_fma_f32 v[4:5], v[18:19], v[218:219], v[4:5]
	v_add_f32_dpp v2, v2, v2 quad_perm:[1,0,3,2] row_mask:0xf bank_mask:0xf bound_ctrl:1
	v_add_f32_e32 v11, v4, v5
	ds_read_b128 v[216:219], v30 offset:7168
	v_add_f32_dpp v2, v2, v2 quad_perm:[2,3,0,1] row_mask:0xf bank_mask:0xf bound_ctrl:1
	ds_read_b128 v[220:223], v30 offset:7424
	ds_read_b128 v[224:227], v30 offset:7680
	v_add_f32_dpp v2, v2, v2 row_half_mirror row_mask:0xf bank_mask:0xf bound_ctrl:1
	ds_read_b128 v[228:231], v30 offset:7936
	v_cndmask_b32_e64 v6, v9, v8, s[12:13]
	v_add_f32_dpp v2, v2, v2 row_mirror row_mask:0xf bank_mask:0xf bound_ctrl:1
	v_cndmask_b32_e64 v7, v8, v9, s[12:13]
	v_cndmask_b32_e64 v55, v11, v10, s[12:13]
	v_cndmask_b32_e64 v57, v10, v11, s[12:13]
	v_pk_fma_f32 v[12:13], v[2:3], v[180:181], v[12:13] op_sel_hi:[0,1,1] neg_lo:[1,0,0] neg_hi:[1,0,0]
	v_pk_fma_f32 v[14:15], v[2:3], v[182:183], v[14:15] op_sel_hi:[0,1,1] neg_lo:[1,0,0] neg_hi:[1,0,0]
	v_pk_mul_f32 v[0:1], v[12:13], v[192:193]
	v_pk_fma_f32 v[16:17], v[104:105], v[188:189], v[12:13] op_sel:[1,0,0]
	v_pk_fma_f32 v[0:1], v[14:15], v[194:195], v[0:1]
	v_pk_fma_f32 v[18:19], v[104:105], v[190:191], v[14:15] op_sel:[1,0,0]
	v_add_f32_e32 v2, v0, v1
	v_pk_mul_f32 v[4:5], v[168:169], v[12:13]
	v_pk_fma_f32 v[4:5], v[14:15], v[170:171], v[4:5]
	v_add_f32_dpp v2, v2, v2 quad_perm:[1,0,3,2] row_mask:0xf bank_mask:0xf bound_ctrl:1
	v_add_f32_e32 v24, v4, v5
	ds_read_b128 v[168:171], v30 offset:8192
	v_add_f32_dpp v2, v2, v2 quad_perm:[2,3,0,1] row_mask:0xf bank_mask:0xf bound_ctrl:1
	ds_read_b128 v[172:175], v30 offset:8448
	ds_read_b128 v[176:179], v30 offset:8704
	v_add_f32_dpp v2, v2, v2 row_half_mirror row_mask:0xf bank_mask:0xf bound_ctrl:1
	ds_read_b128 v[180:183], v30 offset:8960
	v_add_f32_dpp v6, v7, v6 quad_perm:[1,0,3,2] row_mask:0xf bank_mask:0xf bound_ctrl:1
	v_add_f32_dpp v2, v2, v2 row_mirror row_mask:0xf bank_mask:0xf bound_ctrl:1
	v_add_f32_dpp v55, v57, v55 quad_perm:[1,0,3,2] row_mask:0xf bank_mask:0xf bound_ctrl:1
	v_cndmask_b32_e64 v57, v6, v55, s[14:15]
	v_cndmask_b32_e64 v7, v55, v6, s[14:15]
	v_pk_fma_f32 v[16:17], v[2:3], v[196:197], v[16:17] op_sel_hi:[0,1,1] neg_lo:[1,0,0] neg_hi:[1,0,0]
	v_pk_fma_f32 v[18:19], v[2:3], v[198:199], v[18:19] op_sel_hi:[0,1,1] neg_lo:[1,0,0] neg_hi:[1,0,0]
	s_waitcnt lgkmcnt(4)
	v_pk_mul_f32 v[0:1], v[16:17], v[208:209]
	v_pk_fma_f32 v[12:13], v[106:107], v[204:205], v[16:17] op_sel_hi:[0,1,1]
	v_pk_fma_f32 v[0:1], v[18:19], v[210:211], v[0:1]
	v_pk_fma_f32 v[14:15], v[106:107], v[206:207], v[18:19] op_sel_hi:[0,1,1]
	v_add_f32_e32 v2, v0, v1
	v_pk_mul_f32 v[4:5], v[184:185], v[16:17]
	v_pk_fma_f32 v[4:5], v[18:19], v[186:187], v[4:5]
	v_add_f32_dpp v2, v2, v2 quad_perm:[1,0,3,2] row_mask:0xf bank_mask:0xf bound_ctrl:1
	v_add_f32_e32 v25, v4, v5
	ds_read_b128 v[184:187], v30 offset:9216
	v_add_f32_dpp v2, v2, v2 quad_perm:[2,3,0,1] row_mask:0xf bank_mask:0xf bound_ctrl:1
	ds_read_b128 v[188:191], v30 offset:9472
	ds_read_b128 v[192:195], v30 offset:9728
	v_add_f32_dpp v2, v2, v2 row_half_mirror row_mask:0xf bank_mask:0xf bound_ctrl:1
	ds_read_b128 v[196:199], v30 offset:9984
	v_add_f32_dpp v7, v57, v7 quad_perm:[2,3,0,1] row_mask:0xf bank_mask:0xf bound_ctrl:1
	v_add_f32_dpp v2, v2, v2 row_mirror row_mask:0xf bank_mask:0xf bound_ctrl:1
	ds_read_b128 v[64:67], v49 offset:32
	v_add_u32_e32 v49, 32, v49
	v_add_f32_dpp v7, v7, v7 row_ror:4 row_mask:0xf bank_mask:0xf bound_ctrl:1
	v_pk_fma_f32 v[12:13], v[2:3], v[212:213], v[12:13] op_sel_hi:[0,1,1] neg_lo:[1,0,0] neg_hi:[1,0,0]
	v_pk_fma_f32 v[14:15], v[2:3], v[214:215], v[14:15] op_sel_hi:[0,1,1] neg_lo:[1,0,0] neg_hi:[1,0,0]
	v_pk_mul_f32 v[0:1], v[12:13], v[224:225]
	v_pk_fma_f32 v[16:17], v[106:107], v[220:221], v[12:13] op_sel:[1,0,0]
	v_pk_fma_f32 v[0:1], v[14:15], v[226:227], v[0:1]
	v_pk_fma_f32 v[18:19], v[106:107], v[222:223], v[14:15] op_sel:[1,0,0]
	v_add_f32_e32 v2, v0, v1
	v_pk_mul_f32 v[4:5], v[200:201], v[12:13]
	v_pk_fma_f32 v[4:5], v[14:15], v[202:203], v[4:5]
	v_add_f32_dpp v2, v2, v2 quad_perm:[1,0,3,2] row_mask:0xf bank_mask:0xf bound_ctrl:1
	v_add_f32_e32 v26, v4, v5
	ds_read_b128 v[200:203], v30 offset:10240
	v_add_f32_dpp v2, v2, v2 quad_perm:[2,3,0,1] row_mask:0xf bank_mask:0xf bound_ctrl:1
	ds_read_b128 v[204:207], v30 offset:10496
	ds_read_b128 v[208:211], v30 offset:10752
	v_add_f32_dpp v2, v2, v2 row_half_mirror row_mask:0xf bank_mask:0xf bound_ctrl:1
	ds_read_b128 v[212:215], v30 offset:11008
	v_add_f32_dpp v7, v7, v7 row_ror:8 row_mask:0xf bank_mask:0xf bound_ctrl:1
	v_add_f32_dpp v2, v2, v2 row_mirror row_mask:0xf bank_mask:0xf bound_ctrl:1
	ds_write_b32 v53, v7
	v_pk_fma_f32 v[16:17], v[2:3], v[228:229], v[16:17] op_sel_hi:[0,1,1] neg_lo:[1,0,0] neg_hi:[1,0,0]
	v_pk_fma_f32 v[18:19], v[2:3], v[230:231], v[18:19] op_sel_hi:[0,1,1] neg_lo:[1,0,0] neg_hi:[1,0,0]
	v_add_u32_e32 v30, 0x2000, v30
.LrwU_last:
	s_barrier
	s_xor_b32 s37, s30, 1
	s_lshl_b32 s36, s37, 15
	v_or_b32_e32 v20, s36, v69
	s_lshl_b32 s36, s37, 11
	v_add_u32_e32 v21, s36, v92
	v_lshl_add_u32 v22, s37, 8, v95
	s_waitcnt lgkmcnt(5)
	v_pk_mul_f32 v[0:1], v[16:17], v[176:177]
	v_pk_fma_f32 v[12:13], v[64:65], v[172:173], v[16:17] op_sel_hi:[0,1,1]
	v_pk_fma_f32 v[0:1], v[18:19], v[178:179], v[0:1]
	v_pk_fma_f32 v[14:15], v[64:65], v[174:175], v[18:19] op_sel_hi:[0,1,1]
	v_add_f32_e32 v2, v0, v1
	v_pk_mul_f32 v[4:5], v[216:217], v[16:17]
	v_pk_fma_f32 v[4:5], v[18:19], v[218:219], v[4:5]
	v_add_f32_dpp v2, v2, v2 quad_perm:[1,0,3,2] row_mask:0xf bank_mask:0xf bound_ctrl:1
	v_add_f32_e32 v27, v4, v5
	ds_read_b128 v[216:219], v30 offset:3072
	v_add_f32_dpp v2, v2, v2 quad_perm:[2,3,0,1] row_mask:0xf bank_mask:0xf bound_ctrl:1
	ds_read_b128 v[220:223], v30 offset:3328
	ds_read_b128 v[224:227], v30 offset:3584
	v_add_f32_dpp v2, v2, v2 row_half_mirror row_mask:0xf bank_mask:0xf bound_ctrl:1
	ds_read_b128 v[228:231], v30 offset:3840
	v_cndmask_b32_e64 v6, v25, v24, s[12:13]
	v_add_f32_dpp v2, v2, v2 row_mirror row_mask:0xf bank_mask:0xf bound_ctrl:1
	v_cndmask_b32_e64 v7, v24, v25, s[12:13]
	v_cndmask_b32_e64 v55, v27, v26, s[12:13]
	v_cndmask_b32_e64 v57, v26, v27, s[12:13]
	v_pk_fma_f32 v[12:13], v[2:3], v[180:181], v[12:13] op_sel_hi:[0,1,1] neg_lo:[1,0,0] neg_hi:[1,0,0]
	v_pk_fma_f32 v[14:15], v[2:3], v[182:183], v[14:15] op_sel_hi:[0,1,1] neg_lo:[1,0,0] neg_hi:[1,0,0]
	v_pk_mul_f32 v[0:1], v[12:13], v[192:193]
	v_pk_fma_f32 v[16:17], v[64:65], v[188:189], v[12:13] op_sel:[1,0,0]
	v_pk_fma_f32 v[0:1], v[14:15], v[194:195], v[0:1]
	v_pk_fma_f32 v[18:19], v[64:65], v[190:191], v[14:15] op_sel:[1,0,0]
	v_add_f32_e32 v2, v0, v1
	v_pk_mul_f32 v[4:5], v[168:169], v[12:13]
	v_pk_fma_f32 v[4:5], v[14:15], v[170:171], v[4:5]
	v_add_f32_dpp v2, v2, v2 quad_perm:[1,0,3,2] row_mask:0xf bank_mask:0xf bound_ctrl:1
	v_add_f32_e32 v8, v4, v5
	ds_read_b128 v[168:171], v30 offset:4096
	v_add_f32_dpp v2, v2, v2 quad_perm:[2,3,0,1] row_mask:0xf bank_mask:0xf bound_ctrl:1
	ds_read_b128 v[172:175], v30 offset:4352
	ds_read_b128 v[176:179], v30 offset:4608
	v_add_f32_dpp v2, v2, v2 row_half_mirror row_mask:0xf bank_mask:0xf bound_ctrl:1
	ds_read_b128 v[180:183], v30 offset:4864
	v_add_f32_dpp v6, v7, v6 quad_perm:[1,0,3,2] row_mask:0xf bank_mask:0xf bound_ctrl:1
	v_add_f32_dpp v2, v2, v2 row_mirror row_mask:0xf bank_mask:0xf bound_ctrl:1
	v_add_f32_dpp v55, v57, v55 quad_perm:[1,0,3,2] row_mask:0xf bank_mask:0xf bound_ctrl:1
	v_cndmask_b32_e64 v57, v6, v55, s[14:15]
	v_cndmask_b32_e64 v7, v55, v6, s[14:15]
	v_pk_fma_f32 v[16:17], v[2:3], v[196:197], v[16:17] op_sel_hi:[0,1,1] neg_lo:[1,0,0] neg_hi:[1,0,0]
	v_pk_fma_f32 v[18:19], v[2:3], v[198:199], v[18:19] op_sel_hi:[0,1,1] neg_lo:[1,0,0] neg_hi:[1,0,0]
	s_waitcnt lgkmcnt(4)
	v_pk_mul_f32 v[0:1], v[16:17], v[208:209]
	v_pk_fma_f32 v[12:13], v[66:67], v[204:205], v[16:17] op_sel_hi:[0,1,1]
	v_pk_fma_f32 v[0:1], v[18:19], v[210:211], v[0:1]
	v_pk_fma_f32 v[14:15], v[66:67], v[206:207], v[18:19] op_sel_hi:[0,1,1]
	v_add_f32_e32 v2, v0, v1
	v_pk_mul_f32 v[4:5], v[184:185], v[16:17]
	v_pk_fma_f32 v[4:5], v[18:19], v[186:187], v[4:5]
	v_add_f32_dpp v2, v2, v2 quad_perm:[1,0,3,2] row_mask:0xf bank_mask:0xf bound_ctrl:1
	v_add_f32_e32 v9, v4, v5
	ds_read_b128 v[184:187], v30 offset:5120
	v_add_f32_dpp v2, v2, v2 quad_perm:[2,3,0,1] row_mask:0xf bank_mask:0xf bound_ctrl:1
	ds_read_b128 v[188:191], v30 offset:5376
	ds_read_b128 v[192:195], v30 offset:5632
	v_add_f32_dpp v2, v2, v2 row_half_mirror row_mask:0xf bank_mask:0xf bound_ctrl:1
	ds_read_b128 v[196:199], v30 offset:5888
	v_add_f32_dpp v7, v57, v7 quad_perm:[2,3,0,1] row_mask:0xf bank_mask:0xf bound_ctrl:1
	v_add_f32_dpp v2, v2, v2 row_mirror row_mask:0xf bank_mask:0xf bound_ctrl:1
	ds_read_b128 v[104:107], v49 offset:16
	v_add_f32_dpp v7, v7, v7 row_ror:4 row_mask:0xf bank_mask:0xf bound_ctrl:1
	v_pk_fma_f32 v[12:13], v[2:3], v[212:213], v[12:13] op_sel_hi:[0,1,1] neg_lo:[1,0,0] neg_hi:[1,0,0]
	v_pk_fma_f32 v[14:15], v[2:3], v[214:215], v[14:15] op_sel_hi:[0,1,1] neg_lo:[1,0,0] neg_hi:[1,0,0]
	v_pk_mul_f32 v[0:1], v[12:13], v[224:225]
	v_pk_fma_f32 v[16:17], v[66:67], v[220:221], v[12:13] op_sel:[1,0,0]
	v_pk_fma_f32 v[0:1], v[14:15], v[226:227], v[0:1]
	v_pk_fma_f32 v[18:19], v[66:67], v[222:223], v[14:15] op_sel:[1,0,0]
	v_add_f32_e32 v2, v0, v1
	v_pk_mul_f32 v[4:5], v[200:201], v[12:13]
	v_pk_fma_f32 v[4:5], v[14:15], v[202:203], v[4:5]
	v_add_f32_dpp v2, v2, v2 quad_perm:[1,0,3,2] row_mask:0xf bank_mask:0xf bound_ctrl:1
	v_add_f32_e32 v10, v4, v5
	ds_read_b128 v[200:203], v30 offset:6144
	v_add_f32_dpp v2, v2, v2 quad_perm:[2,3,0,1] row_mask:0xf bank_mask:0xf bound_ctrl:1
	ds_read_b128 v[204:207], v30 offset:6400
	ds_read_b128 v[208:211], v30 offset:6656
	v_add_f32_dpp v2, v2, v2 row_half_mirror row_mask:0xf bank_mask:0xf bound_ctrl:1
	ds_read_b128 v[212:215], v30 offset:6912
	v_add_f32_dpp v7, v7, v7 row_ror:8 row_mask:0xf bank_mask:0xf bound_ctrl:1
	v_add_f32_dpp v2, v2, v2 row_mirror row_mask:0xf bank_mask:0xf bound_ctrl:1
	ds_write_b32 v53, v7 offset:256
	v_add_u32_e32 v53, 0x200, v53
	v_pk_fma_f32 v[16:17], v[2:3], v[228:229], v[16:17] op_sel_hi:[0,1,1] neg_lo:[1,0,0] neg_hi:[1,0,0]
	v_pk_fma_f32 v[18:19], v[2:3], v[230:231], v[18:19] op_sel_hi:[0,1,1] neg_lo:[1,0,0] neg_hi:[1,0,0]
	s_waitcnt lgkmcnt(5)
	v_pk_mul_f32 v[0:1], v[16:17], v[176:177]
	v_pk_fma_f32 v[12:13], v[104:105], v[172:173], v[16:17] op_sel_hi:[0,1,1]
	v_pk_fma_f32 v[0:1], v[18:19], v[178:179], v[0:1]
	v_pk_fma_f32 v[14:15], v[104:105], v[174:175], v[18:19] op_sel_hi:[0,1,1]
	v_add_f32_e32 v2, v0, v1
	v_pk_mul_f32 v[4:5], v[216:217], v[16:17]
	v_pk_fma_f32 v[4:5], v[18:19], v[218:219], v[4:5]
	v_add_f32_dpp v2, v2, v2 quad_perm:[1,0,3,2] row_mask:0xf bank_mask:0xf bound_ctrl:1
	v_add_f32_e32 v11, v4, v5
	ds_read_b128 v[216:219], v30 offset:7168
	v_add_f32_dpp v2, v2, v2 quad_perm:[2,3,0,1] row_mask:0xf bank_mask:0xf bound_ctrl:1
	ds_read_b128 v[220:223], v30 offset:7424
	ds_read_b128 v[224:227], v30 offset:7680
	v_add_f32_dpp v2, v2, v2 row_half_mirror row_mask:0xf bank_mask:0xf bound_ctrl:1
	ds_read_b128 v[228:231], v30 offset:7936
	v_cndmask_b32_e64 v6, v9, v8, s[12:13]
	v_add_f32_dpp v2, v2, v2 row_mirror row_mask:0xf bank_mask:0xf bound_ctrl:1
	v_cndmask_b32_e64 v7, v8, v9, s[12:13]
	v_cndmask_b32_e64 v55, v11, v10, s[12:13]
	v_cndmask_b32_e64 v57, v10, v11, s[12:13]
	v_pk_fma_f32 v[12:13], v[2:3], v[180:181], v[12:13] op_sel_hi:[0,1,1] neg_lo:[1,0,0] neg_hi:[1,0,0]
	v_pk_fma_f32 v[14:15], v[2:3], v[182:183], v[14:15] op_sel_hi:[0,1,1] neg_lo:[1,0,0] neg_hi:[1,0,0]
	v_pk_mul_f32 v[0:1], v[12:13], v[192:193]
	v_pk_fma_f32 v[16:17], v[104:105], v[188:189], v[12:13] op_sel:[1,0,0]
	v_pk_fma_f32 v[0:1], v[14:15], v[194:195], v[0:1]
	v_pk_fma_f32 v[18:19], v[104:105], v[190:191], v[14:15] op_sel:[1,0,0]
	v_add_f32_e32 v2, v0, v1
	v_pk_mul_f32 v[4:5], v[168:169], v[12:13]
	v_pk_fma_f32 v[4:5], v[14:15], v[170:171], v[4:5]
	v_add_f32_dpp v2, v2, v2 quad_perm:[1,0,3,2] row_mask:0xf bank_mask:0xf bound_ctrl:1
	v_add_f32_e32 v24, v4, v5
	ds_read_b128 v[168:171], v20
	v_add_f32_dpp v2, v2, v2 quad_perm:[2,3,0,1] row_mask:0xf bank_mask:0xf bound_ctrl:1
	ds_read_b128 v[172:175], v20 offset:256
	ds_read_b128 v[176:179], v20 offset:512
	v_add_f32_dpp v2, v2, v2 row_half_mirror row_mask:0xf bank_mask:0xf bound_ctrl:1
	ds_read_b128 v[180:183], v20 offset:768
	v_add_f32_dpp v6, v7, v6 quad_perm:[1,0,3,2] row_mask:0xf bank_mask:0xf bound_ctrl:1
	v_add_f32_dpp v2, v2, v2 row_mirror row_mask:0xf bank_mask:0xf bound_ctrl:1
	v_add_f32_dpp v55, v57, v55 quad_perm:[1,0,3,2] row_mask:0xf bank_mask:0xf bound_ctrl:1
	v_cndmask_b32_e64 v57, v6, v55, s[14:15]
	v_cndmask_b32_e64 v7, v55, v6, s[14:15]
	v_pk_fma_f32 v[16:17], v[2:3], v[196:197], v[16:17] op_sel_hi:[0,1,1] neg_lo:[1,0,0] neg_hi:[1,0,0]
	v_pk_fma_f32 v[18:19], v[2:3], v[198:199], v[18:19] op_sel_hi:[0,1,1] neg_lo:[1,0,0] neg_hi:[1,0,0]
	s_waitcnt lgkmcnt(4)
	v_pk_mul_f32 v[0:1], v[16:17], v[208:209]
	v_pk_fma_f32 v[12:13], v[106:107], v[204:205], v[16:17] op_sel_hi:[0,1,1]
	v_pk_fma_f32 v[0:1], v[18:19], v[210:211], v[0:1]
	v_pk_fma_f32 v[14:15], v[106:107], v[206:207], v[18:19] op_sel_hi:[0,1,1]
	v_add_f32_e32 v2, v0, v1
	v_pk_mul_f32 v[4:5], v[184:185], v[16:17]
	v_pk_fma_f32 v[4:5], v[18:19], v[186:187], v[4:5]
	v_add_f32_dpp v2, v2, v2 quad_perm:[1,0,3,2] row_mask:0xf bank_mask:0xf bound_ctrl:1
	v_add_f32_e32 v25, v4, v5
	ds_read_b128 v[184:187], v20 offset:1024
	v_add_f32_dpp v2, v2, v2 quad_perm:[2,3,0,1] row_mask:0xf bank_mask:0xf bound_ctrl:1
	ds_read_b128 v[188:191], v20 offset:1280
	ds_read_b128 v[192:195], v20 offset:1536
	v_add_f32_dpp v2, v2, v2 row_half_mirror row_mask:0xf bank_mask:0xf bound_ctrl:1
	ds_read_b128 v[196:199], v20 offset:1792
	v_add_f32_dpp v7, v57, v7 quad_perm:[2,3,0,1] row_mask:0xf bank_mask:0xf bound_ctrl:1
	v_add_f32_dpp v2, v2, v2 row_mirror row_mask:0xf bank_mask:0xf bound_ctrl:1
	ds_read_b128 v[64:67], v21
	v_add_u32_e32 v49, 32, v49
	v_add_f32_dpp v7, v7, v7 row_ror:4 row_mask:0xf bank_mask:0xf bound_ctrl:1
	v_pk_fma_f32 v[12:13], v[2:3], v[212:213], v[12:13] op_sel_hi:[0,1,1] neg_lo:[1,0,0] neg_hi:[1,0,0]
	v_pk_fma_f32 v[14:15], v[2:3], v[214:215], v[14:15] op_sel_hi:[0,1,1] neg_lo:[1,0,0] neg_hi:[1,0,0]
	v_pk_mul_f32 v[0:1], v[12:13], v[224:225]
	v_pk_fma_f32 v[16:17], v[106:107], v[220:221], v[12:13] op_sel:[1,0,0]
	v_pk_fma_f32 v[0:1], v[14:15], v[226:227], v[0:1]
	v_pk_fma_f32 v[18:19], v[106:107], v[222:223], v[14:15] op_sel:[1,0,0]
	v_add_f32_e32 v2, v0, v1
	v_pk_mul_f32 v[4:5], v[200:201], v[12:13]
	v_pk_fma_f32 v[4:5], v[14:15], v[202:203], v[4:5]
	v_add_f32_dpp v2, v2, v2 quad_perm:[1,0,3,2] row_mask:0xf bank_mask:0xf bound_ctrl:1
	v_add_f32_e32 v26, v4, v5
	ds_read_b128 v[200:203], v20 offset:2048
	v_add_f32_dpp v2, v2, v2 quad_perm:[2,3,0,1] row_mask:0xf bank_mask:0xf bound_ctrl:1
	ds_read_b128 v[204:207], v20 offset:2304
	ds_read_b128 v[208:211], v20 offset:2560
	v_add_f32_dpp v2, v2, v2 row_half_mirror row_mask:0xf bank_mask:0xf bound_ctrl:1
	ds_read_b128 v[212:215], v20 offset:2816
	v_add_f32_dpp v7, v7, v7 row_ror:8 row_mask:0xf bank_mask:0xf bound_ctrl:1
	v_add_f32_dpp v2, v2, v2 row_mirror row_mask:0xf bank_mask:0xf bound_ctrl:1
	ds_read_b128 v[112:115], v22
	ds_write_b32 v53, v7
	v_pk_fma_f32 v[16:17], v[2:3], v[228:229], v[16:17] op_sel_hi:[0,1,1] neg_lo:[1,0,0] neg_hi:[1,0,0]
	v_pk_fma_f32 v[18:19], v[2:3], v[230:231], v[18:19] op_sel_hi:[0,1,1] neg_lo:[1,0,0] neg_hi:[1,0,0]
.LrwU_drain:
	v_pk_mul_f32 v[4:5], v[216:217], v[16:17]
	v_pk_fma_f32 v[4:5], v[18:19], v[218:219], v[4:5]
	s_nop 0
	v_add_f32_e32 v27, v4, v5
	v_cndmask_b32_e64 v6, v25, v24, s[12:13]
	v_cndmask_b32_e64 v7, v24, v25, s[12:13]
	v_cndmask_b32_e64 v55, v27, v26, s[12:13]
	v_cndmask_b32_e64 v57, v26, v27, s[12:13]
	v_add_f32_dpp v6, v7, v6 quad_perm:[1,0,3,2] row_mask:0xf bank_mask:0xf bound_ctrl:1
	v_pk_mul_f32 v[16:17], v[16:17], v[108:109]
	v_add_f32_dpp v55, v57, v55 quad_perm:[1,0,3,2] row_mask:0xf bank_mask:0xf bound_ctrl:1
	v_cndmask_b32_e64 v57, v6, v55, s[14:15]
	v_cndmask_b32_e64 v7, v55, v6, s[14:15]
	v_pk_mul_f32 v[18:19], v[18:19], v[110:111]
	v_add_f32_dpp v7, v57, v7 quad_perm:[2,3,0,1] row_mask:0xf bank_mask:0xf bound_ctrl:1
	s_add_i32 s26, s26, 1
	s_cmpk_eq_i32 s26, 0x201
	v_add_f32_dpp v7, v7, v7 row_ror:4 row_mask:0xf bank_mask:0xf bound_ctrl:1
	s_nop 1
	v_add_f32_dpp v7, v7, v7 row_ror:8 row_mask:0xf bank_mask:0xf bound_ctrl:1
	ds_write_b32 v53, v7 offset:256
	s_waitcnt lgkmcnt(0)
	s_barrier
	s_cbranch_scc1 .LrwU_done
	s_and_b32 s30, s26, 1
	s_lshl_b32 s36, s30, 11
	s_lshl_b32 s37, s30, 15
	v_or_b32_e32 v30, s37, v69
	v_add_u32_e32 v49, s36, v92
	v_add_u32_e32 v1, s36, v94
	v_cndmask_b32_e64 v53, v93, v1, s[24:25]
	s_lshl_b32 s27, s26, 5
	s_sub_i32 s27, 0x4010, s27
	s_min_u32 s27, s27, 32
	s_lshr_b32 s36, s27, 3
	v_mov_b64_e32 v[108:109], v[112:113]
	v_mov_b64_e32 v[110:111], v[114:115]
	s_branch .LrwU_first
.LrwU_done:
	s_setprio 0
	s_lshl_b32 s22, s2, 14
	s_and_b32 s22, s22, 0x7c000
	s_add_u32 s22, s67, s22
	v_lshl_or_b32 v0, s47, 10, v70
	s_addc_u32 s23, s92, 0
	v_ashrrev_i32_e32 v1, 31, v0
	v_lshl_add_u64 v[0:1], v[0:1], 2, s[22:23]
	v_mov_b32_e32 v55, v31
	v_lshl_add_u64 v[0:1], v[0:1], 0, v[54:55]
	global_store_dwordx4 v[0:1], v[16:19], off
	s_branch .LBB0_451
